# speedup vs baseline: 1.0363x; 1.0013x over previous
; #define LAS __attribute__((address_space(3)))
; template <int MODE>
; __device__ __forceinline__ void attn_unit(LAS unsigned char* lds, const bf16_t* __restrict__ qkvz, bf16_t* __restrict__ A2, const int b, const int hd, const int qb, const AttnX& X, const int tid) {
;     ...
;         f32x16 S0, S1;
;         if (active) {
; #pragma unroll
;             for (int i = 0; i < 16; ++i) { S0[i] = 0.f; S1[i] = 0.f; }
;             const LAS unsigned char* kb = lds + cur * STG + kbase_off;
;             __builtin_amdgcn_s_setprio(1);
; #pragma unroll
;             for (int s = 0; s < NS; ++s) {
;                 const bf16x8 a0 = *(const LAS bf16x8*)(kb + s * 32);
;                 const bf16x8 a1 = *(const LAS bf16x8*)(kb + 32 * PK + s * 32);
;                 S0 = __builtin_amdgcn_mfma_f32_32x32x16_bf16(a0, qf[s], S0, 0, 0, 0);
;                 S1 = __builtin_amdgcn_mfma_f32_32x32x16_bf16(a1, qf[s], S1, 0, 0, 0);
;             }
;             __builtin_amdgcn_s_setprio(0);
;         }
.LBB0_1041:
	s_mul_i32 s11, s2, 0x9400
	v_add_u32_e32 v0, s11, v178
	s_setprio 1
	ds_read_b128 v[146:149], v0
	ds_read_b128 v[234:237], v0 offset:8704
	ds_read_b128 v[238:241], v0 offset:32
	ds_read_b128 v[242:245], v0 offset:8736
	ds_read_b128 v[246:249], v0 offset:64
	ds_read_b128 v[250:253], v0 offset:8768
	s_waitcnt lgkmcnt(5)
	v_mfma_f32_32x32x16_bf16 v[66:81], v[146:149], v[98:101], 0
	ds_read_b128 v[146:149], v0 offset:96
	s_waitcnt lgkmcnt(5)
	v_mfma_f32_32x32x16_bf16 v[82:97], v[234:237], v[98:101], 0
	ds_read_b128 v[234:237], v0 offset:8800
	s_waitcnt lgkmcnt(5)
	v_mfma_f32_32x32x16_bf16 v[66:81], v[238:241], v[102:105], v[66:81]
	ds_read_b128 v[238:241], v0 offset:128
	s_waitcnt lgkmcnt(5)
	v_mfma_f32_32x32x16_bf16 v[82:97], v[242:245], v[102:105], v[82:97]
	ds_read_b128 v[242:245], v0 offset:8832
	s_waitcnt lgkmcnt(5)
	v_mfma_f32_32x32x16_bf16 v[66:81], v[246:249], v[106:109], v[66:81]
	ds_read_b128 v[246:249], v0 offset:160
	s_waitcnt lgkmcnt(5)
	v_mfma_f32_32x32x16_bf16 v[82:97], v[250:253], v[106:109], v[82:97]
	ds_read_b128 v[250:253], v0 offset:8864
	s_waitcnt lgkmcnt(5)
	v_mfma_f32_32x32x16_bf16 v[66:81], v[146:149], v[110:113], v[66:81]
	ds_read_b128 v[146:149], v0 offset:192
	s_waitcnt lgkmcnt(5)
	v_mfma_f32_32x32x16_bf16 v[82:97], v[234:237], v[110:113], v[82:97]
	ds_read_b128 v[234:237], v0 offset:8896
	s_waitcnt lgkmcnt(5)
	v_mfma_f32_32x32x16_bf16 v[66:81], v[238:241], v[114:117], v[66:81]
	ds_read_b128 v[238:241], v0 offset:224
	s_waitcnt lgkmcnt(5)
	v_mfma_f32_32x32x16_bf16 v[82:97], v[242:245], v[114:117], v[82:97]
	ds_read_b128 v[242:245], v0 offset:8928
	s_waitcnt lgkmcnt(5)
	v_mfma_f32_32x32x16_bf16 v[66:81], v[246:249], v[118:121], v[66:81]
	s_waitcnt lgkmcnt(4)
	v_mfma_f32_32x32x16_bf16 v[82:97], v[250:253], v[118:121], v[82:97]
	s_waitcnt lgkmcnt(3)
	v_mfma_f32_32x32x16_bf16 v[66:81], v[146:149], v[122:125], v[66:81]
	s_waitcnt lgkmcnt(2)
	v_mfma_f32_32x32x16_bf16 v[82:97], v[234:237], v[122:125], v[82:97]
	s_waitcnt lgkmcnt(1)
	v_mfma_f32_32x32x16_bf16 v[66:81], v[238:241], v[126:129], v[66:81]
	s_waitcnt lgkmcnt(0)
	v_mfma_f32_32x32x16_bf16 v[82:97], v[242:245], v[126:129], v[82:97]
	s_setprio 0
	v_cndmask_b32_e64 v0, 0, 1, s[94:95]
	v_cmp_ne_u32_e64 s[82:83], 1, v0
	s_andn2_b64 vcc, exec, s[94:95]
	s_cbranch_vccnz .LBB0_1038
